# speedup vs baseline: 1.0144x; 1.0120x over previous
; __device__ __forceinline__ unsigned xb_ld(unsigned* p)              { return __hip_atomic_load(p, __ATOMIC_RELAXED, __HIP_MEMORY_SCOPE_AGENT); }
; #define XB_SPIN(cond, bar) do { unsigned _sp = 0; while (cond) { __builtin_amdgcn_s_sleep(1); \
;     if ((++_sp & 255u) == 0u) { if (xb_ld(&(bar)[XB_TMO])) break; if (_sp > XB_SPIN_CAP) { atomicAdd(&(bar)[XB_TMO], 1u); break; } } } } while (0)
; __device__ __forceinline__ void xcd_barrier(unsigned* bar, volatile LAS unsigned* st) {
;     ...
;             __builtin_amdgcn_fence(__ATOMIC_ACQUIRE, "agent");
;             asm volatile("s_waitcnt vmcnt(0)" ::: "memory");
;         } else {
;             XB_SPIN(xb_ld(&bar[XB_XGEN(x)]) == gen, bar);
;             __builtin_amdgcn_fence(__ATOMIC_ACQUIRE, "agent");
;             asm volatile("s_waitcnt vmcnt(0)" ::: "memory");
.LBB0_194:
	s_or_b64 exec, exec, s[6:7]
	s_waitcnt vmcnt(0)
	s_waitcnt vmcnt(0)

; __device__ __forceinline__ unsigned xb_ld(unsigned* p)              { return __hip_atomic_load(p, __ATOMIC_RELAXED, __HIP_MEMORY_SCOPE_AGENT); }
; __device__ __forceinline__ unsigned xb_add(unsigned* p, unsigned v) { return __hip_atomic_fetch_add(p, v, __ATOMIC_RELAXED, __HIP_MEMORY_SCOPE_AGENT); }
; #define XB_SPIN(cond, bar) do { unsigned _sp = 0; while (cond) { __builtin_amdgcn_s_sleep(1); \
;     if ((++_sp & 255u) == 0u) { if (xb_ld(&(bar)[XB_TMO])) break; if (_sp > XB_SPIN_CAP) { atomicAdd(&(bar)[XB_TMO], 1u); break; } } } } while (0)
; __device__ __forceinline__ void xcd_barrier(unsigned* bar, volatile LAS unsigned* st) {
;     ...
;         const unsigned old = xb_add(&bar[XB_XSUB(x)], 1u);
;         const unsigned gen = old / nloc;
;         if (old + 1u == (gen + 1u) * nloc) {
;             __builtin_amdgcn_fence(__ATOMIC_RELEASE, "agent");
;             asm volatile("s_waitcnt vmcnt(0)" ::: "memory");
;             const unsigned og = xb_add(&bar[XB_TOP], 1u);
;             const unsigned tg = og / nx;
;             if (og + 1u == (tg + 1u) * nx) xb_add(&bar[XB_TOPGEN], 1u);
;             else XB_SPIN(xb_ld(&bar[XB_TOPGEN]) == tg, bar);
;             xb_add(&bar[XB_XGEN(x)], 1u);
;             __builtin_amdgcn_fence(__ATOMIC_ACQUIRE, "agent");
;             asm volatile("s_waitcnt vmcnt(0)" ::: "memory");
;         } else {
;             XB_SPIN(xb_ld(&bar[XB_XGEN(x)]) == gen, bar);
.LBB0_326:
	s_lshl_b32 s8, s20, 8
	s_mov_b64 s[10:11], exec
	s_add_u32 s8, s6, s8
	s_addc_u32 s9, s7, 0
	v_mbcnt_lo_u32_b32 v2, s10, 0
	s_add_u32 s8, s8, 0x12b90000
	v_mbcnt_hi_u32_b32 v2, s11, v2
	s_addc_u32 s9, s9, 0
	v_cmp_eq_u32_e32 vcc, 0, v2
	s_and_saveexec_b64 s[12:13], vcc
	s_cbranch_execz .LBB0_328
	s_bcnt1_i32_b64 s10, s[10:11]
	v_mov_b32_e32 v4, s10
	v_mov_b32_e32 v5, 0x1000
	global_atomic_add v4, v5, v4, s[8:9] offset:1024 sc0
	buffer_inv sc1
.LBB0_328:
	s_or_b64 exec, exec, s[12:13]
	v_cvt_f32_u32_e32 v5, v3
	s_waitcnt vmcnt(1)
	v_readfirstlane_b32 s10, v4
	v_sub_u32_e32 v4, 0, v3
	v_rcp_iflag_f32_e32 v5, v5
	v_add_u32_e32 v6, s10, v2
	v_mul_f32_e32 v5, 0x4f7ffffe, v5
	v_cvt_u32_f32_e32 v5, v5
	v_mul_lo_u32 v2, v4, v5
	v_mul_hi_u32 v2, v5, v2
	v_add_u32_e32 v2, v5, v2
	v_mul_hi_u32 v2, v6, v2
	v_mul_lo_u32 v4, v2, v3
	v_sub_u32_e32 v4, v6, v4
	v_add_u32_e32 v5, 1, v2
	v_sub_u32_e32 v7, v4, v3
	v_cmp_ge_u32_e32 vcc, v4, v3
	s_nop 1
	v_cndmask_b32_e32 v2, v2, v5, vcc
	v_cndmask_b32_e32 v4, v4, v7, vcc
	v_add_u32_e32 v5, 1, v2
	v_cmp_ge_u32_e32 vcc, v4, v3
	v_add_u32_e32 v4, 1, v6
	s_nop 0
	v_cndmask_b32_e32 v2, v2, v5, vcc
	v_mul_lo_u32 v5, v3, v2
	v_add_u32_e32 v3, v5, v3
	v_cmp_ne_u32_e32 vcc, v4, v3
	s_and_saveexec_b64 s[10:11], vcc
	s_xor_b64 s[10:11], exec, s[10:11]
	s_cbranch_execz .LBB0_342
	s_waitcnt lgkmcnt(0)
	v_mov_b32_e32 v0, 0x2000
	global_load_dword v0, v0, s[8:9] offset:1024 sc1
	s_add_u32 s26, s8, 0x2400
	s_addc_u32 s27, s9, 0
	s_waitcnt vmcnt(0)
	v_cmp_eq_u32_e32 vcc, v0, v2
	s_and_saveexec_b64 s[12:13], vcc
	s_cbranch_execz .LBB0_341
	s_add_u32 s16, s6, 0x12b90200
	s_addc_u32 s17, s7, 0
	s_mov_b32 s20, 1
	s_mov_b64 s[28:29], 0
	s_branch .LBB0_332

; __device__ __forceinline__ unsigned xb_ld(unsigned* p)              { return __hip_atomic_load(p, __ATOMIC_RELAXED, __HIP_MEMORY_SCOPE_AGENT); }
; #define XB_SPIN(cond, bar) do { unsigned _sp = 0; while (cond) { __builtin_amdgcn_s_sleep(1); \
;     if ((++_sp & 255u) == 0u) { if (xb_ld(&(bar)[XB_TMO])) break; if (_sp > XB_SPIN_CAP) { atomicAdd(&(bar)[XB_TMO], 1u); break; } } } } while (0)
; __device__ __forceinline__ void xcd_barrier(unsigned* bar, volatile LAS unsigned* st) {
;     ...
;             XB_SPIN(xb_ld(&bar[XB_XGEN(x)]) == gen, bar);
;             __builtin_amdgcn_fence(__ATOMIC_ACQUIRE, "agent");
;             asm volatile("s_waitcnt vmcnt(0)" ::: "memory");
.LBB0_341:
	s_or_b64 exec, exec, s[12:13]
	s_waitcnt vmcnt(0)
	s_waitcnt vmcnt(0)

; __device__ __forceinline__ unsigned xb_add(unsigned* p, unsigned v) { return __hip_atomic_fetch_add(p, v, __ATOMIC_RELAXED, __HIP_MEMORY_SCOPE_AGENT); }
; __device__ __forceinline__ void xcd_barrier(unsigned* bar, volatile LAS unsigned* st) {
;     ...
;             xb_add(&bar[XB_XGEN(x)], 1u);
;             __builtin_amdgcn_fence(__ATOMIC_ACQUIRE, "agent");
;             asm volatile("s_waitcnt vmcnt(0)" ::: "memory");
.Lxl_skip_gu:
	v_mov_b32_e32 v0, 1
	v_mov_b32_e32 v2, 0x2000
	global_atomic_add v2, v0, s[8:9] offset:1024
	s_waitcnt vmcnt(0)
	s_branch .LBB0_362

; __device__ __forceinline__ unsigned xb_ld(unsigned* p)              { return __hip_atomic_load(p, __ATOMIC_RELAXED, __HIP_MEMORY_SCOPE_AGENT); }
; __device__ __forceinline__ unsigned xb_add(unsigned* p, unsigned v) { return __hip_atomic_fetch_add(p, v, __ATOMIC_RELAXED, __HIP_MEMORY_SCOPE_AGENT); }
; #define XB_SPIN(cond, bar) do { unsigned _sp = 0; while (cond) { __builtin_amdgcn_s_sleep(1); \
;     if ((++_sp & 255u) == 0u) { if (xb_ld(&(bar)[XB_TMO])) break; if (_sp > XB_SPIN_CAP) { atomicAdd(&(bar)[XB_TMO], 1u); break; } } } } while (0)
; __device__ __forceinline__ void xcd_barrier(unsigned* bar, volatile LAS unsigned* st) {
;     ...
;         const unsigned old = xb_add(&bar[XB_XSUB(x)], 1u);
;         const unsigned gen = old / nloc;
;         if (old + 1u == (gen + 1u) * nloc) {
;             __builtin_amdgcn_fence(__ATOMIC_RELEASE, "agent");
;             asm volatile("s_waitcnt vmcnt(0)" ::: "memory");
;             const unsigned og = xb_add(&bar[XB_TOP], 1u);
;             const unsigned tg = og / nx;
;             if (og + 1u == (tg + 1u) * nx) xb_add(&bar[XB_TOPGEN], 1u);
;             else XB_SPIN(xb_ld(&bar[XB_TOPGEN]) == tg, bar);
;             xb_add(&bar[XB_XGEN(x)], 1u);
;             __builtin_amdgcn_fence(__ATOMIC_ACQUIRE, "agent");
;             asm volatile("s_waitcnt vmcnt(0)" ::: "memory");
;         } else {
;             XB_SPIN(xb_ld(&bar[XB_XGEN(x)]) == gen, bar);
.LBB0_419:
	s_lshl_b32 s10, s20, 8
	s_mov_b64 s[12:13], exec
	s_add_u32 s10, s8, s10
	s_addc_u32 s11, s9, 0
	v_mbcnt_lo_u32_b32 v0, s12, 0
	s_add_u32 s10, s10, 0x12b90000
	v_mbcnt_hi_u32_b32 v0, s13, v0
	s_addc_u32 s11, s11, 0
	v_cmp_eq_u32_e32 vcc, 0, v0
	s_and_saveexec_b64 s[16:17], vcc
	s_cbranch_execz .LBB0_421
	s_bcnt1_i32_b64 s12, s[12:13]
	v_mov_b32_e32 v4, s12
	v_mov_b32_e32 v5, 0x1000
	global_atomic_add v4, v5, v4, s[10:11] offset:1024 sc0
	buffer_inv sc1
.LBB0_421:
	s_or_b64 exec, exec, s[16:17]
	v_cvt_f32_u32_e32 v5, v3
	s_waitcnt vmcnt(1)
	v_readfirstlane_b32 s12, v4
	v_sub_u32_e32 v4, 0, v3
	v_rcp_iflag_f32_e32 v5, v5
	v_add_u32_e32 v6, s12, v0
	v_mul_f32_e32 v5, 0x4f7ffffe, v5
	v_cvt_u32_f32_e32 v5, v5
	v_mul_lo_u32 v0, v4, v5
	v_mul_hi_u32 v0, v5, v0
	v_add_u32_e32 v0, v5, v0
	v_mul_hi_u32 v0, v6, v0
	v_mul_lo_u32 v4, v0, v3
	v_sub_u32_e32 v4, v6, v4
	v_add_u32_e32 v5, 1, v0
	v_cmp_ge_u32_e32 vcc, v4, v3
	s_nop 1
	v_cndmask_b32_e32 v0, v0, v5, vcc
	v_sub_u32_e32 v5, v4, v3
	v_cndmask_b32_e32 v4, v4, v5, vcc
	v_add_u32_e32 v5, 1, v0
	v_cmp_ge_u32_e32 vcc, v4, v3
	v_add_u32_e32 v4, 1, v6
	s_nop 0
	v_cndmask_b32_e32 v0, v0, v5, vcc
	v_mul_lo_u32 v5, v3, v0
	v_add_u32_e32 v3, v5, v3
	v_cmp_ne_u32_e32 vcc, v4, v3
	s_and_saveexec_b64 s[12:13], vcc
	s_xor_b64 s[16:17], exec, s[12:13]
	s_cbranch_execz .LBB0_435
	s_waitcnt lgkmcnt(0)
	v_mov_b32_e32 v2, 0x2000
	global_load_dword v2, v2, s[10:11] offset:1024 sc1
	s_add_u32 s28, s10, 0x2400
	s_addc_u32 s29, s11, 0
	s_waitcnt vmcnt(0)
	v_cmp_eq_u32_e32 vcc, v2, v0
	s_and_saveexec_b64 s[12:13], vcc
	s_cbranch_execz .LBB0_434
	s_add_u32 s26, s8, 0x12b90200
	s_addc_u32 s27, s9, 0
	s_mov_b32 s20, 1
	s_mov_b64 s[30:31], 0
	s_branch .LBB0_425

; __device__ __forceinline__ unsigned xb_add(unsigned* p, unsigned v) { return __hip_atomic_fetch_add(p, v, __ATOMIC_RELAXED, __HIP_MEMORY_SCOPE_AGENT); }
; __device__ __forceinline__ void xcd_barrier(unsigned* bar, volatile LAS unsigned* st) {
;     ...
;             xb_add(&bar[XB_XGEN(x)], 1u);
;             __builtin_amdgcn_fence(__ATOMIC_ACQUIRE, "agent");
;             asm volatile("s_waitcnt vmcnt(0)" ::: "memory");
.Lxl_skip_d:
	v_mov_b32_e32 v0, 1
	v_mov_b32_e32 v2, 0x2000
	global_atomic_add v2, v0, s[10:11] offset:1024
	s_waitcnt vmcnt(0)
	s_branch .LBB0_455

; __device__ __forceinline__ unsigned xb_ld(unsigned* p)              { return __hip_atomic_load(p, __ATOMIC_RELAXED, __HIP_MEMORY_SCOPE_AGENT); }
; __device__ __forceinline__ unsigned xb_add(unsigned* p, unsigned v) { return __hip_atomic_fetch_add(p, v, __ATOMIC_RELAXED, __HIP_MEMORY_SCOPE_AGENT); }
; #define XB_SPIN(cond, bar) do { unsigned _sp = 0; while (cond) { __builtin_amdgcn_s_sleep(1); \
;     if ((++_sp & 255u) == 0u) { if (xb_ld(&(bar)[XB_TMO])) break; if (_sp > XB_SPIN_CAP) { atomicAdd(&(bar)[XB_TMO], 1u); break; } } } } while (0)
; __device__ __forceinline__ void xcd_barrier(unsigned* bar, volatile LAS unsigned* st) {
;     ...
;         const unsigned old = xb_add(&bar[XB_XSUB(x)], 1u);
;         const unsigned gen = old / nloc;
;         if (old + 1u == (gen + 1u) * nloc) {
;             __builtin_amdgcn_fence(__ATOMIC_RELEASE, "agent");
;             asm volatile("s_waitcnt vmcnt(0)" ::: "memory");
;             const unsigned og = xb_add(&bar[XB_TOP], 1u);
;             const unsigned tg = og / nx;
;             if (og + 1u == (tg + 1u) * nx) xb_add(&bar[XB_TOPGEN], 1u);
;             else XB_SPIN(xb_ld(&bar[XB_TOPGEN]) == tg, bar);
;             xb_add(&bar[XB_XGEN(x)], 1u);
;             __builtin_amdgcn_fence(__ATOMIC_ACQUIRE, "agent");
;             asm volatile("s_waitcnt vmcnt(0)" ::: "memory");
;         } else {
;             XB_SPIN(xb_ld(&bar[XB_XGEN(x)]) == gen, bar);
.LBB0_904:
	s_lshl_b32 s8, s20, 8
	s_mov_b64 s[10:11], exec
	s_add_u32 s8, s6, s8
	s_addc_u32 s9, s7, 0
	v_mbcnt_lo_u32_b32 v0, s10, 0
	s_add_u32 s8, s8, 0x12b90000
	v_mbcnt_hi_u32_b32 v0, s11, v0
	s_addc_u32 s9, s9, 0
	v_cmp_eq_u32_e32 vcc, 0, v0
	s_and_saveexec_b64 s[12:13], vcc
	s_cbranch_execz .LBB0_906
	s_bcnt1_i32_b64 s10, s[10:11]
	v_mov_b32_e32 v4, s10
	v_mov_b32_e32 v5, 0x1000
	global_atomic_add v4, v5, v4, s[8:9] offset:1024 sc0
	buffer_inv sc1
.LBB0_906:
	s_or_b64 exec, exec, s[12:13]
	v_cvt_f32_u32_e32 v5, v3
	s_waitcnt vmcnt(1)
	v_readfirstlane_b32 s10, v4
	v_sub_u32_e32 v4, 0, v3
	v_rcp_iflag_f32_e32 v5, v5
	v_add_u32_e32 v6, s10, v0
	v_mul_f32_e32 v5, 0x4f7ffffe, v5
	v_cvt_u32_f32_e32 v5, v5
	v_mul_lo_u32 v0, v4, v5
	v_mul_hi_u32 v0, v5, v0
	v_add_u32_e32 v0, v5, v0
	v_mul_hi_u32 v0, v6, v0
	v_mul_lo_u32 v4, v0, v3
	v_sub_u32_e32 v4, v6, v4
	v_add_u32_e32 v5, 1, v0
	v_cmp_ge_u32_e32 vcc, v4, v3
	s_nop 1
	v_cndmask_b32_e32 v0, v0, v5, vcc
	v_sub_u32_e32 v5, v4, v3
	v_cndmask_b32_e32 v4, v4, v5, vcc
	v_add_u32_e32 v5, 1, v0
	v_cmp_ge_u32_e32 vcc, v4, v3
	v_add_u32_e32 v4, 1, v6
	s_nop 0
	v_cndmask_b32_e32 v0, v0, v5, vcc
	v_mul_lo_u32 v5, v3, v0
	v_add_u32_e32 v3, v5, v3
	v_cmp_ne_u32_e32 vcc, v4, v3
	s_and_saveexec_b64 s[10:11], vcc
	s_xor_b64 s[10:11], exec, s[10:11]
	s_cbranch_execz .LBB0_920
	s_waitcnt lgkmcnt(0)
	v_mov_b32_e32 v2, 0x2000
	global_load_dword v2, v2, s[8:9] offset:1024 sc1
	s_add_u32 s26, s8, 0x2400
	s_addc_u32 s27, s9, 0
	s_waitcnt vmcnt(0)
	v_cmp_eq_u32_e32 vcc, v2, v0
	s_and_saveexec_b64 s[12:13], vcc
	s_cbranch_execz .LBB0_919
	s_add_u32 s16, s6, 0x12b90200
	s_addc_u32 s17, s7, 0
	s_mov_b32 s20, 1
	s_mov_b64 s[28:29], 0
	s_branch .LBB0_910
